# MLA fixed-shift loop unrolled by two; K/V tiles loaded two tiles ahead into two alternating register sets, each top waits only for its own set (counted vmcnt)
# baseline (speedup 1.0000x reference)
.LBB0_1186:
	s_or_b64 exec, exec, s[2:3]
	v_lshlrev_b64 v[2:3], 6, v[24:25]
	v_lshlrev_b32_e32 v4, 3, v32
	v_lshl_add_u64 v[2:3], v[2:3], 1, v[12:13]
	v_lshlrev_b32_e32 v4, 1, v4
	v_mov_b32_e32 v5, v113
	v_lshl_add_u64 v[2:3], v[2:3], 0, v[4:5]
	v_add_co_u32_e32 v2, vcc, 0x2000, v2
	v_and_b32_e32 v6, 31, v29
	s_nop 0
	v_addc_co_u32_e32 v3, vcc, 0, v3, vcc
	global_load_dwordx4 v[204:207], v[2:3], off
	v_mul_u32_u24_e32 v2, 0xd0, v6
	v_add3_u32 v180, 0, v2, v22
	s_waitcnt lgkmcnt(0)
	s_barrier
	ds_read_b128 v[2:5], v180
	ds_read_b128 v[12:15], v180 offset:32
	v_xor_b32_e32 v32, 0x80000000, v28
	v_mov_b32_e32 v33, v32
	v_mov_b32_e32 v34, v32
	v_mov_b32_e32 v35, v32
	v_mov_b32_e32 v36, v32
	v_mov_b32_e32 v37, v32
	v_mov_b32_e32 v38, v32
	v_mov_b32_e32 v39, v32
	v_mov_b32_e32 v40, v32
	v_mov_b32_e32 v41, v32
	v_mov_b32_e32 v42, v32
	v_mov_b32_e32 v43, v32
	v_mov_b32_e32 v44, v32
	v_mov_b32_e32 v45, v32
	v_mov_b32_e32 v46, v32
	v_mov_b32_e32 v47, v32
	v_lshl_add_u64 v[0:1], v[0:1], 0, v[10:11]
	v_lshl_add_u64 v[0:1], v[18:19], 1, v[0:1]
	s_waitcnt lgkmcnt(0)
	v_mfma_f32_32x32x16_bf16 v[64:79], v[2:5], v[100:103], v[32:47]
	ds_read_b128 v[2:5], v180 offset:6656
	ds_read_b128 v[24:27], v180 offset:6688
	v_lshl_add_u64 v[142:143], s[12:13], 0, v[0:1]
	v_mad_i64_i32 v[0:1], s[2:3], v23, s22, v[10:11]
	v_lshlrev_b32_e32 v177, 2, v30
	v_lshrrev_b32_e32 v6, 2, v29
	v_lshl_add_u64 v[0:1], v[16:17], 1, v[0:1]
	s_waitcnt lgkmcnt(0)
	v_mfma_f32_32x32x16_bf16 v[48:63], v[2:5], v[100:103], v[32:47]
	v_and_or_b32 v6, v6, 3, v177
	v_lshlrev_b32_e32 v7, 1, v29
	v_lshl_add_u64 v[162:163], s[12:13], 0, v[0:1]
	v_lshl_add_u64 v[0:1], v[8:9], 0, v[20:21]
	v_mad_u32_u24 v6, v6, s20, 0
	v_and_b32_e32 v7, 32, v7
	v_lshl_add_u64 v[0:1], v[0:1], 0, v[112:113]
	v_mfma_f32_32x32x16_bf16 v[64:79], v[12:15], v[104:107], v[64:79]
	ds_read_b128 v[2:5], v180 offset:64
	ds_read_b128 v[12:15], v180 offset:96
	v_mov_b32_e32 v114, 0
	v_and_b32_e32 v178, 63, v29
	s_mov_b32 s34, 0
	v_add_u32_e32 v173, -3, v166
	v_lshl_add_u64 v[164:165], s[14:15], 0, v[0:1]
	s_mov_b64 s[2:3], 0
	v_mfma_f32_32x32x16_bf16 v[48:63], v[24:27], v[104:107], v[48:63]
	v_mov_b32_e32 v0, 0
	v_mov_b32_e32 v1, v114
	v_mov_b32_e32 v8, v114
	v_mov_b32_e32 v9, v114
	v_mov_b32_e32 v10, v114
	v_mov_b32_e32 v11, v114
	v_mov_b32_e32 v16, 0
	s_waitcnt lgkmcnt(0)
	v_mfma_f32_32x32x16_bf16 v[64:79], v[2:5], v[108:111], v[64:79]
	ds_read_b128 v[2:5], v180 offset:6720
	ds_read_b128 v[24:27], v180 offset:6752
	v_mov_b32_e32 v17, v114
	v_mov_b32_e32 v18, v114
	v_mov_b32_e32 v19, v114
	v_mov_b32_e32 v20, v114
	v_mov_b32_e32 v21, v114
	v_mov_b32_e32 v22, v114
	s_waitcnt lgkmcnt(0)
	v_mfma_f32_32x32x16_bf16 v[48:63], v[2:5], v[108:111], v[48:63]
	ds_read_b128 v[2:5], v180 offset:128
	ds_read_b128 v[80:83], v180 offset:160
	ds_read_b128 v[84:87], v180 offset:6784
	ds_read_b128 v[88:91], v180 offset:6816
	v_mov_b32_e32 v23, v114
	v_mov_b32_e32 v28, v114
	v_mov_b32_e32 v30, v114
	v_mov_b32_e32 v31, v114
	s_waitcnt lgkmcnt(0)
	s_barrier
	v_mfma_f32_32x32x16_bf16 v[64:79], v[12:15], v[116:119], v[64:79]
	v_lshlrev_b32_e32 v12, 3, v29
	v_and_b32_e32 v12, 24, v12
	v_add3_u32 v179, v6, v7, v12
	v_mov_b32_e32 v6, v114
	v_mov_b32_e32 v7, v114
	v_mov_b32_e32 v12, v114
	v_mov_b32_e32 v13, v114
	v_mfma_f32_32x32x16_bf16 v[48:63], v[24:27], v[116:119], v[48:63]
	v_mov_b32_e32 v14, v114
	v_mov_b32_e32 v15, v114
	v_mov_b32_e32 v24, v114
	v_mov_b32_e32 v25, v114
	v_mov_b32_e32 v26, v114
	v_mov_b32_e32 v27, v114
	v_mov_b32_e32 v29, v114
	v_mfma_f32_32x32x16_bf16 v[64:79], v[2:5], v[120:123], v[64:79]
	v_mov_b32_e32 v2, v114
	v_mov_b32_e32 v3, v114
	v_mov_b32_e32 v4, v114
	v_mov_b32_e32 v5, v114
	v_mfma_f32_32x32x16_bf16 v[48:63], v[84:87], v[120:123], v[48:63]
	v_mfma_f32_32x32x16_bf16 v[64:79], v[80:83], v[96:99], v[64:79]
	v_mfma_f32_32x32x16_bf16 v[48:63], v[88:91], v[96:99], v[48:63]
	global_load_dwordx4 v[208:211], v[162:163], off
	s_and_saveexec_b64 s[36:37], s[6:7]
	s_cbranch_execz .Lmla_pro_set1
	global_load_dwordx4 v[212:215], v[142:143], off
.Lmla_pro_set1:
	s_or_b64 exec, exec, s[36:37]
	global_load_dwordx4 v[216:219], v[164:165], off
	v_lshl_add_u64 v[162:163], v[162:163], 0, s[24:25]
	v_lshl_add_u64 v[142:143], v[142:143], 0, s[24:25]
	v_lshl_add_u64 v[164:165], v[164:165], 0, s[0:1]
	v_readfirstlane_b32 s99, v246
	s_lshr_b32 s99, s99, 8
	s_branch .LBB0_1188
.LBB0_1187:
	s_or_b64 exec, exec, s[36:37]
	s_add_i32 s34, s34, 1
	s_bitcmp1_b32 s34, 0
	s_cselect_b32 s36, 0x3400, 0
	v_add_u32_e32 v112, s36, v180
	ds_read_b128 v[132:135], v112
	ds_read_b128 v[136:139], v112 offset:32
	v_exp_f32_e32 v174, v48
	v_exp_f32_e32 v175, v49
	v_exp_f32_e32 v182, v50
	s_waitcnt lgkmcnt(0)
	v_mfma_f32_32x32x16_bf16 v[80:95], v[132:135], v[100:103], v[32:47]
	v_exp_f32_e32 v183, v51
	v_exp_f32_e32 v184, v52
	v_exp_f32_e32 v185, v53
	v_exp_f32_e32 v186, v54
	v_exp_f32_e32 v187, v55
	v_exp_f32_e32 v188, v56
	v_exp_f32_e32 v189, v57
	v_mfma_f32_32x32x16_bf16 v[80:95], v[136:139], v[104:107], v[80:95]
	ds_read_b128 v[132:135], v112 offset:64
	ds_read_b128 v[136:139], v112 offset:96
	v_exp_f32_e32 v190, v58
	v_exp_f32_e32 v191, v59
	v_exp_f32_e32 v192, v60
	v_exp_f32_e32 v193, v61
	v_exp_f32_e32 v194, v62
	v_exp_f32_e32 v195, v63
	s_waitcnt lgkmcnt(0)
	v_mfma_f32_32x32x16_bf16 v[80:95], v[132:135], v[108:111], v[80:95]
	ds_read_b128 v[132:135], v112 offset:128
	ds_read_b128 v[48:51], v112 offset:160
	s_and_b64 s[18:19], s[18:19], exec
	s_cselect_b32 s18, 0x2400, 0
	v_exp_f32_e32 v198, v64
	v_exp_f32_e32 v199, v65
	v_exp_f32_e32 v200, v70
	v_mfma_f32_32x32x16_bf16 v[80:95], v[136:139], v[116:119], v[80:95]
	v_exp_f32_e32 v201, v71
	v_exp_f32_e32 v202, v72
	v_exp_f32_e32 v203, v73
	v_exp_f32_e32 v76, v76
	v_cvt_pk_bf16_f32 v71, v200, v201
	v_exp_f32_e32 v78, v78
	v_exp_f32_e32 v79, v79
	s_waitcnt lgkmcnt(0)
	v_mfma_f32_32x32x16_bf16 v[80:95], v[132:135], v[120:123], v[80:95]
	ds_read_b128 v[132:135], v112 offset:6656
	ds_read_b128 v[146:149], v112 offset:6688
	v_exp_f32_e32 v77, v77
	v_cmp_eq_u32_e32 vcc, s34, v173
	v_lshl_add_u64 v[142:143], v[142:143], 0, s[24:25]
	v_lshl_add_u64 v[162:163], v[162:163], 0, s[24:25]
	s_or_b64 s[2:3], vcc, s[2:3]
	v_mfma_f32_32x32x16_bf16 v[80:95], v[48:51], v[96:99], v[80:95]
	s_waitcnt lgkmcnt(0)
	v_mfma_f32_32x32x16_bf16 v[48:63], v[132:135], v[100:103], v[32:47]
	ds_read_b128 v[150:153], v112 offset:6720
	ds_read_b128 v[154:157], v112 offset:6752
	ds_read_b128 v[158:161], v112 offset:6784
	ds_read_b128 v[136:139], v112 offset:6816
	v_add_u32_e32 v112, s18, v179
	v_lshl_add_u64 v[164:165], v[164:165], 0, s[0:1]
	v_mfma_f32_32x32x16_bf16 v[48:63], v[146:149], v[104:107], v[48:63]
	v_exp_f32_e32 v146, v66
	v_exp_f32_e32 v147, v67
	v_exp_f32_e32 v148, v68
	v_exp_f32_e32 v149, v69
	ds_read_b64_tr_b16 v[64:65], v112 offset:26624
	ds_read_b64_tr_b16 v[66:67], v112 offset:27776
	v_cvt_pk_bf16_f32 v68, v198, v199
	v_cvt_pk_bf16_f32 v69, v146, v147
	s_waitcnt lgkmcnt(0)
	v_mfma_f32_32x32x16_bf16 v[48:63], v[150:153], v[108:111], v[48:63]
	v_exp_f32_e32 v150, v74
	v_exp_f32_e32 v151, v75
	ds_read_b64_tr_b16 v[74:75], v112 offset:27840
	ds_read_b64_tr_b16 v[72:73], v112 offset:26688
	v_cvt_pk_bf16_f32 v70, v148, v149
	v_pk_add_f32 v[146:147], v[182:183], v[146:147]
	v_pk_add_f32 v[198:199], v[174:175], v[198:199]
	v_pk_add_f32 v[148:149], v[184:185], v[148:149]
	v_mfma_f32_32x32x16_bf16 v[0:15], v[64:67], v[68:71], v[0:15]
	ds_read_b64_tr_b16 v[64:65], v112 offset:28928
	ds_read_b64_tr_b16 v[66:67], v112 offset:30080
	v_add_f32_e64 v152, v194, v78
	v_add_f32_e64 v153, v195, v79
	s_waitcnt lgkmcnt(0)
	v_mfma_f32_32x32x16_bf16 v[16:31], v[72:75], v[68:71], v[16:31]
	ds_read_b64_tr_b16 v[74:75], v112 offset:30144
	ds_read_b64_tr_b16 v[72:73], v112 offset:28992
	v_cvt_pk_bf16_f32 v68, v202, v203
	v_cvt_pk_bf16_f32 v69, v150, v151
	v_cvt_pk_bf16_f32 v70, v76, v77
	v_cvt_pk_bf16_f32 v71, v78, v79
	v_mfma_f32_32x32x16_bf16 v[48:63], v[154:157], v[116:119], v[48:63]
	v_add_f32_e64 v154, v192, v76
	v_add_f32_e64 v155, v193, v77
	v_add_f32_e64 v156, v190, v150
	v_add_f32_e64 v157, v191, v151
	v_mfma_f32_32x32x16_bf16 v[0:15], v[64:67], v[68:71], v[0:15]
	s_waitcnt lgkmcnt(0)
	v_mfma_f32_32x32x16_bf16 v[16:31], v[72:75], v[68:71], v[16:31]
	v_cvt_pk_bf16_f32 v68, v174, v175
	v_cvt_pk_bf16_f32 v69, v182, v183
	v_cvt_pk_bf16_f32 v70, v184, v185
	v_cvt_pk_bf16_f32 v71, v186, v187
	v_mfma_f32_32x32x16_bf16 v[48:63], v[158:161], v[120:123], v[48:63]
	v_add_f32_e64 v160, v186, v200
	v_add_f32_e64 v161, v187, v201
	v_pk_mov_b32 v[200:201], v[198:199], v[146:147] op_sel:[1,0]
	v_mov_b32_e32 v199, v147
	v_pk_add_f32 v[64:65], v[200:201], v[198:199]
	v_pk_mov_b32 v[78:79], v[148:149], v[160:161] op_sel:[1,0]
	v_pk_add_f32 v[76:77], v[64:65], v[64:65] op_sel_hi:[0,1]
	ds_read_b64_tr_b16 v[64:65], v112 offset:31232
	ds_read_b64_tr_b16 v[66:67], v112 offset:32384
	ds_read_b64_tr_b16 v[74:75], v112 offset:32448
	ds_read_b64_tr_b16 v[72:73], v112 offset:31296
	s_waitcnt lgkmcnt(0)
	v_mfma_f32_32x32x16_bf16 v[0:15], v[64:67], v[68:71], v[0:15]
	ds_read_b64_tr_b16 v[64:65], v112 offset:33536
	ds_read_b64_tr_b16 v[66:67], v112 offset:34688
	v_mov_b32_e32 v149, v161
	v_add_f32_e64 v78, v78, v148
	v_add_f32_e64 v79, v79, v149
	v_pk_add_f32 v[158:159], v[188:189], v[202:203]
	v_pk_add_f32 v[78:79], v[78:79], v[78:79] op_sel_hi:[0,1]
	v_add_f32_e32 v147, v158, v159
	v_add_f32_e32 v149, v156, v157
	v_mfma_f32_32x32x16_bf16 v[16:31], v[72:75], v[68:71], v[16:31]
	ds_read_b64_tr_b16 v[74:75], v112 offset:34752
	ds_read_b64_tr_b16 v[72:73], v112 offset:33600
	v_cvt_pk_bf16_f32 v68, v188, v189
	v_cvt_pk_bf16_f32 v69, v190, v191
	v_cvt_pk_bf16_f32 v70, v192, v193
	v_cvt_pk_bf16_f32 v71, v194, v195
	v_mov_b32_e32 v146, v154
	v_mov_b32_e32 v148, v155
	s_waitcnt lgkmcnt(0)
	v_mfma_f32_32x32x16_bf16 v[0:15], v[64:67], v[68:71], v[0:15]
	v_mov_b32_e32 v76, v152
	v_mov_b32_e32 v78, v153
	v_add_f32_e64 v146, v146, v148
	v_add_f32_e64 v147, v147, v149
	v_add_f32_e64 v64, v76, v78
	v_add_f32_e64 v65, v77, v79
	v_pk_add_f32 v[64:65], v[146:147], v[64:65]
	s_barrier
	v_mfma_f32_32x32x16_bf16 v[16:31], v[72:75], v[68:71], v[16:31]
	v_add_f32_e32 v64, v64, v65
	v_add_f32_e32 v114, v114, v64
	v_mfma_f32_32x32x16_bf16 v[48:63], v[136:139], v[96:99], v[48:63]
	s_andn2_b64 exec, exec, s[2:3]
	s_cbranch_execz .Lmla_exit_e
.Lmla_top_o:
	s_bitcmp1_b32 s34, 0
	s_cselect_b64 s[18:19], -1, 0
	s_and_b64 s[36:37], s[18:19], exec
	s_cselect_b32 s36, 0x3400, 0
	s_add_i32 s46, s36, 0
	v_add3_u32 v112, s46, v168, v170
	s_cmp_eq_u32 s99, 0
	s_cbranch_scc1 .Lmla_w3_o
	s_waitcnt vmcnt(2)
	s_branch .Lmla_wd_o
.Lmla_w3_o:
	s_waitcnt vmcnt(3)
.Lmla_wd_o:
	ds_write_b128 v112, v[208:211]
	s_and_saveexec_b64 s[36:37], s[6:7]
	v_add3_u32 v112, s46, v171, v172
	ds_write_b128 v112, v[212:215]
	s_or_b64 exec, exec, s[36:37]
	s_andn2_b32 s36, 1, s34
	s_mulk_i32 s36, 0x2400
	v_add_u32_e32 v112, s36, v115
	ds_write_b128 v112, v[216:219] offset:26624
	global_load_dwordx4 v[216:219], v[164:165], off
	global_load_dwordx4 v[208:211], v[162:163], off
	s_and_saveexec_b64 s[36:37], s[6:7]
	s_cbranch_execz .Lmla_body_o
	global_load_dwordx4 v[212:215], v[142:143], off
	s_branch .Lmla_body_o
.Lmla_body_o:
	s_or_b64 exec, exec, s[36:37]
	s_add_i32 s34, s34, 1
	s_bitcmp1_b32 s34, 0
	s_cselect_b32 s36, 0x3400, 0
	v_add_u32_e32 v112, s36, v180
	ds_read_b128 v[132:135], v112
	ds_read_b128 v[136:139], v112 offset:32
	v_exp_f32_e32 v174, v48
	v_exp_f32_e32 v175, v49
	v_exp_f32_e32 v182, v50
	s_waitcnt lgkmcnt(0)
	v_mfma_f32_32x32x16_bf16 v[64:79], v[132:135], v[100:103], v[32:47]
	v_exp_f32_e32 v183, v51
	v_exp_f32_e32 v184, v52
	v_exp_f32_e32 v185, v53
	v_exp_f32_e32 v186, v54
	v_exp_f32_e32 v187, v55
	v_exp_f32_e32 v188, v56
	v_exp_f32_e32 v189, v57
	v_mfma_f32_32x32x16_bf16 v[64:79], v[136:139], v[104:107], v[64:79]
	ds_read_b128 v[132:135], v112 offset:64
	ds_read_b128 v[136:139], v112 offset:96
	v_exp_f32_e32 v190, v58
	v_exp_f32_e32 v191, v59
	v_exp_f32_e32 v192, v60
	v_exp_f32_e32 v193, v61
	v_exp_f32_e32 v194, v62
	v_exp_f32_e32 v195, v63
	s_waitcnt lgkmcnt(0)
	v_mfma_f32_32x32x16_bf16 v[64:79], v[132:135], v[108:111], v[64:79]
	ds_read_b128 v[132:135], v112 offset:128
	ds_read_b128 v[48:51], v112 offset:160
	s_and_b64 s[18:19], s[18:19], exec
	s_cselect_b32 s18, 0x2400, 0
	v_exp_f32_e32 v198, v80
	v_exp_f32_e32 v199, v81
	v_exp_f32_e32 v200, v86
	v_mfma_f32_32x32x16_bf16 v[64:79], v[136:139], v[116:119], v[64:79]
	v_exp_f32_e32 v201, v87
	v_exp_f32_e32 v202, v88
	v_exp_f32_e32 v203, v89
	v_exp_f32_e32 v92, v92
	v_cvt_pk_bf16_f32 v87, v200, v201
	v_exp_f32_e32 v94, v94
	v_exp_f32_e32 v95, v95
	s_waitcnt lgkmcnt(0)
	v_mfma_f32_32x32x16_bf16 v[64:79], v[132:135], v[120:123], v[64:79]
	ds_read_b128 v[132:135], v112 offset:6656
	ds_read_b128 v[146:149], v112 offset:6688
	v_exp_f32_e32 v93, v93
	v_cmp_eq_u32_e32 vcc, s34, v173
	v_lshl_add_u64 v[142:143], v[142:143], 0, s[24:25]
	v_lshl_add_u64 v[162:163], v[162:163], 0, s[24:25]
	s_or_b64 s[2:3], vcc, s[2:3]
	v_mfma_f32_32x32x16_bf16 v[64:79], v[48:51], v[96:99], v[64:79]
	s_waitcnt lgkmcnt(0)
	v_mfma_f32_32x32x16_bf16 v[48:63], v[132:135], v[100:103], v[32:47]
	ds_read_b128 v[150:153], v112 offset:6720
	ds_read_b128 v[154:157], v112 offset:6752
	ds_read_b128 v[158:161], v112 offset:6784
	ds_read_b128 v[136:139], v112 offset:6816
	v_add_u32_e32 v112, s18, v179
	v_lshl_add_u64 v[164:165], v[164:165], 0, s[0:1]
	v_mfma_f32_32x32x16_bf16 v[48:63], v[146:149], v[104:107], v[48:63]
	v_exp_f32_e32 v146, v82
	v_exp_f32_e32 v147, v83
	v_exp_f32_e32 v148, v84
	v_exp_f32_e32 v149, v85
	ds_read_b64_tr_b16 v[80:81], v112 offset:26624
	ds_read_b64_tr_b16 v[82:83], v112 offset:27776
	v_cvt_pk_bf16_f32 v84, v198, v199
	v_cvt_pk_bf16_f32 v85, v146, v147
	s_waitcnt lgkmcnt(0)
	v_mfma_f32_32x32x16_bf16 v[48:63], v[150:153], v[108:111], v[48:63]
	v_exp_f32_e32 v150, v90
	v_exp_f32_e32 v151, v91
	ds_read_b64_tr_b16 v[90:91], v112 offset:27840
	ds_read_b64_tr_b16 v[88:89], v112 offset:26688
	v_cvt_pk_bf16_f32 v86, v148, v149
	v_pk_add_f32 v[146:147], v[182:183], v[146:147]
	v_pk_add_f32 v[198:199], v[174:175], v[198:199]
	v_pk_add_f32 v[148:149], v[184:185], v[148:149]
	v_mfma_f32_32x32x16_bf16 v[0:15], v[80:83], v[84:87], v[0:15]
	ds_read_b64_tr_b16 v[80:81], v112 offset:28928
	ds_read_b64_tr_b16 v[82:83], v112 offset:30080
	v_add_f32_e64 v152, v194, v94
	v_add_f32_e64 v153, v195, v95
	s_waitcnt lgkmcnt(0)
	v_mfma_f32_32x32x16_bf16 v[16:31], v[88:91], v[84:87], v[16:31]
	ds_read_b64_tr_b16 v[90:91], v112 offset:30144
	ds_read_b64_tr_b16 v[88:89], v112 offset:28992
	v_cvt_pk_bf16_f32 v84, v202, v203
	v_cvt_pk_bf16_f32 v85, v150, v151
	v_cvt_pk_bf16_f32 v86, v92, v93
	v_cvt_pk_bf16_f32 v87, v94, v95
	v_mfma_f32_32x32x16_bf16 v[48:63], v[154:157], v[116:119], v[48:63]
	v_add_f32_e64 v154, v192, v92
	v_add_f32_e64 v155, v193, v93
	v_add_f32_e64 v156, v190, v150
	v_add_f32_e64 v157, v191, v151
	v_mfma_f32_32x32x16_bf16 v[0:15], v[80:83], v[84:87], v[0:15]
	s_waitcnt lgkmcnt(0)
	v_mfma_f32_32x32x16_bf16 v[16:31], v[88:91], v[84:87], v[16:31]
	v_cvt_pk_bf16_f32 v84, v174, v175
	v_cvt_pk_bf16_f32 v85, v182, v183
	v_cvt_pk_bf16_f32 v86, v184, v185
	v_cvt_pk_bf16_f32 v87, v186, v187
	v_mfma_f32_32x32x16_bf16 v[48:63], v[158:161], v[120:123], v[48:63]
	v_add_f32_e64 v160, v186, v200
	v_add_f32_e64 v161, v187, v201
	v_pk_mov_b32 v[200:201], v[198:199], v[146:147] op_sel:[1,0]
	v_mov_b32_e32 v199, v147
	v_pk_add_f32 v[80:81], v[200:201], v[198:199]
	v_pk_mov_b32 v[94:95], v[148:149], v[160:161] op_sel:[1,0]
	v_pk_add_f32 v[92:93], v[80:81], v[80:81] op_sel_hi:[0,1]
	ds_read_b64_tr_b16 v[80:81], v112 offset:31232
	ds_read_b64_tr_b16 v[82:83], v112 offset:32384
	ds_read_b64_tr_b16 v[90:91], v112 offset:32448
	ds_read_b64_tr_b16 v[88:89], v112 offset:31296
	s_waitcnt lgkmcnt(0)
	v_mfma_f32_32x32x16_bf16 v[0:15], v[80:83], v[84:87], v[0:15]
	ds_read_b64_tr_b16 v[80:81], v112 offset:33536
	ds_read_b64_tr_b16 v[82:83], v112 offset:34688
	v_mov_b32_e32 v149, v161
	v_add_f32_e64 v94, v94, v148
	v_add_f32_e64 v95, v95, v149
	v_pk_add_f32 v[158:159], v[188:189], v[202:203]
	v_pk_add_f32 v[94:95], v[94:95], v[94:95] op_sel_hi:[0,1]
	v_add_f32_e32 v147, v158, v159
	v_add_f32_e32 v149, v156, v157
	v_mfma_f32_32x32x16_bf16 v[16:31], v[88:91], v[84:87], v[16:31]
	ds_read_b64_tr_b16 v[90:91], v112 offset:34752
	ds_read_b64_tr_b16 v[88:89], v112 offset:33600
	v_cvt_pk_bf16_f32 v84, v188, v189
	v_cvt_pk_bf16_f32 v85, v190, v191
	v_cvt_pk_bf16_f32 v86, v192, v193
	v_cvt_pk_bf16_f32 v87, v194, v195
	v_mov_b32_e32 v146, v154
	v_mov_b32_e32 v148, v155
	s_waitcnt lgkmcnt(0)
	v_mfma_f32_32x32x16_bf16 v[0:15], v[80:83], v[84:87], v[0:15]
	v_mov_b32_e32 v92, v152
	v_mov_b32_e32 v94, v153
	v_add_f32_e64 v146, v146, v148
	v_add_f32_e64 v147, v147, v149
	v_add_f32_e64 v80, v92, v94
	v_add_f32_e64 v81, v93, v95
	v_pk_add_f32 v[80:81], v[146:147], v[80:81]
	s_barrier
	v_mfma_f32_32x32x16_bf16 v[16:31], v[88:91], v[84:87], v[16:31]
	v_add_f32_e32 v80, v80, v81
	v_add_f32_e32 v114, v114, v80
	v_mfma_f32_32x32x16_bf16 v[48:63], v[136:139], v[96:99], v[48:63]
	s_andn2_b64 exec, exec, s[2:3]
	s_cbranch_execz .LBB0_1192

.Lmla_wd_e:
	ds_write_b128 v112, v[128:131]
	s_and_saveexec_b64 s[36:37], s[6:7]
	v_add3_u32 v112, s46, v171, v172
	ds_write_b128 v112, v[124:127]
	s_or_b64 exec, exec, s[36:37]
	s_andn2_b32 s36, 1, s34
	s_mulk_i32 s36, 0x2400
	v_add_u32_e32 v112, s36, v115
	ds_write_b128 v112, v[204:207] offset:26624
	global_load_dwordx4 v[204:207], v[164:165], off
	global_load_dwordx4 v[128:131], v[162:163], off
	s_and_saveexec_b64 s[36:37], s[6:7]
	s_cbranch_execz .LBB0_1187
	global_load_dwordx4 v[124:127], v[142:143], off
	s_branch .LBB0_1187
.Lmla_exit_e:
	s_or_b64 exec, exec, s[2:3]
	v_mov_b64_e32 v[64:65], v[80:81]
	v_mov_b64_e32 v[66:67], v[82:83]
	v_mov_b64_e32 v[68:69], v[84:85]
	v_mov_b64_e32 v[70:71], v[86:87]
	v_mov_b64_e32 v[72:73], v[88:89]
	v_mov_b64_e32 v[74:75], v[90:91]
	v_mov_b64_e32 v[76:77], v[92:93]
	v_mov_b64_e32 v[78:79], v[94:95]
	s_waitcnt vmcnt(0)
	v_mov_b32_e32 v128, v208
	v_mov_b32_e32 v129, v209
	v_mov_b32_e32 v130, v210
	v_mov_b32_e32 v131, v211
	v_mov_b32_e32 v124, v212
	v_mov_b32_e32 v125, v213
	v_mov_b32_e32 v126, v214
	v_mov_b32_e32 v127, v215
	v_mov_b32_e32 v132, v216
	v_mov_b32_e32 v133, v217
	v_mov_b32_e32 v134, v218
	v_mov_b32_e32 v135, v219
	s_branch .Lmla_exit_join

.Lmla_exit_join:
	ds_write_b128 v169, v[128:131] offset:13312
	s_and_saveexec_b64 s[2:3], s[6:7]
	s_cbranch_execz .LBB0_1011
	ds_write_b128 v167, v[124:127] offset:13312
	s_branch .LBB0_1011
